# plus first-barrier census: sixteen counter loads in flight under one wait instead of a serial chain
# baseline (speedup 1.0000x reference)
; __device__ __forceinline__ unsigned xb_ld(unsigned* p)              { return __hip_atomic_load(p, __ATOMIC_RELAXED, __HIP_MEMORY_SCOPE_AGENT); }
; __device__ __forceinline__ void xcd_barrier_complete(unsigned* bar, unsigned x, unsigned& nloc, unsigned& nx) {
;     const unsigned G = gridDim.x * gridDim.y * gridDim.z;
;     unsigned sum, cnt, mine, sp = 0u;
;     for (;;) {
;         sum = 0u; cnt = 0u; mine = 0u;
; #pragma unroll
;         for (unsigned j = 0; j < 16; ++j) { const unsigned c = xb_ld(&bar[XB_XCNT(j)]); sum += c; cnt += (c > 0u) ? 1u : 0u; mine = (j == x) ? c : mine; }
;         if (sum == G) break;
;         __builtin_amdgcn_s_sleep(1);
;         if ((++sp & 255u) == 0u) { if (xb_ld(&bar[XB_TMO])) break; if (sp > XB_SPIN_CAP) { atomicAdd(&bar[XB_TMO], 1u); break; } }
;     }
.LBB0_1179:
	v_readlane_b32 s6, v254, 8
	v_readlane_b32 s7, v254, 9
	s_mov_b64 s[20:21], -1
	s_mov_b64 s[22:23], -1
	s_waitcnt lgkmcnt(0)
	s_nop 4
	global_load_dword v0, v1, s[6:7] sc1
	global_load_dword v2, v1, s[6:7] offset:256 sc1
	global_load_dword v3, v1, s[6:7] offset:512 sc1
	global_load_dword v4, v1, s[6:7] offset:768 sc1
	global_load_dword v5, v1, s[6:7] offset:1024 sc1
	global_load_dword v6, v1, s[6:7] offset:1280 sc1
	global_load_dword v7, v1, s[6:7] offset:1536 sc1
	global_load_dword v8, v1, s[6:7] offset:1792 sc1
	global_load_dword v9, v1, s[6:7] offset:2048 sc1
	global_load_dword v10, v1, s[6:7] offset:2304 sc1
	global_load_dword v11, v1, s[6:7] offset:2560 sc1
	global_load_dword v12, v1, s[6:7] offset:2816 sc1
	global_load_dword v13, v1, s[6:7] offset:3072 sc1
	global_load_dword v14, v1, s[6:7] offset:3328 sc1
	global_load_dword v15, v1, s[6:7] offset:3584 sc1
	global_load_dword v16, v1, s[6:7] offset:3840 sc1
	s_waitcnt vmcnt(0)
	v_add_u32_e32 v17, v2, v0
	v_add_u32_e32 v17, v17, v3
	v_add_u32_e32 v17, v17, v4
	v_add_u32_e32 v17, v17, v5
	v_add_u32_e32 v17, v17, v6
	v_add_u32_e32 v17, v17, v7
	v_add_u32_e32 v17, v17, v8
	v_add_u32_e32 v17, v17, v9
	v_add_u32_e32 v17, v17, v10
	v_add_u32_e32 v17, v17, v11
	v_add_u32_e32 v17, v17, v12
	v_add_u32_e32 v17, v17, v13
	v_add_u32_e32 v17, v17, v14
	v_add_u32_e32 v17, v17, v15
	v_add_u32_e32 v17, v17, v16
	v_cmp_eq_u32_e32 vcc, s48, v17
	s_cbranch_vccnz .LBB0_1178
	s_and_b32 s5, s4, 0xff
	s_cmp_eq_u32 s5, 0
	s_mov_b64 s[26:27], -1
	s_sleep 1
	s_cbranch_scc1 .LBB0_1183
	s_and_b64 vcc, exec, s[26:27]
	s_cbranch_vccz .LBB0_1178
